# residual GEMMs (pool/Wo/down) now run both half-workgroup epilogues together (aligned, as the QKV/up GEMMs already do) instead of one after the other
# speedup vs baseline: 1.0162x; 1.0098x over previous
; #define PG8_BAR __builtin_amdgcn_s_barrier()
;     __host__ __device__ bool next(int i, Unit& u) const {
;         long L = (long)i * G + c; if (L >= nwg) return false;
;         if (rev) L = nwg - 1 - L;
;         int wgid = (int)L; { const int q = nwg / NXCD, r = nwg % NXCD, xcd = wgid % NXCD, off = wgid / NXCD; wgid = (xcd < r ? xcd * (q + 1) : r * (q + 1) + (xcd - r) * q) + off; }
;         const int nig = WGM * nN, gid = wgid / nig, fm = gid * WGM, gsz = (nM - fm) < WGM ? (nM - fm) : WGM;
;         u.pm = fm + ((wgid % nig) % gsz); u.pn = (wgid % nig) / gsz; return true;
;     }
; template <class Epi, class Sched, bool ALIGN_EPI = false, bool SP2 = false>
; __device__ __forceinline__ void gemm_phase(PG8_LAS unsigned char* lds, const Gemm g, const Sched& S, const Epi& E, const int tid_in) {
;     ...
;         if constexpr (ALIGN_EPI) { if (wr == 0) PG8_BAR; }
;         if constexpr (!Epi::AFTER_DRAIN) { E(acc, cur, wr, wc, fr, fq); S.done(cur); }
;         if (!has_next) break;
; #pragma unroll
;         for (int a = 0; a < 2; ++a)
; #pragma unroll
;             for (int b = 0; b < 2; ++b)
; #pragma unroll
;                 for (int m = 0; m < 4; ++m)
; #pragma unroll
;                     for (int n = 0; n < 2; ++n) acc[a][b][m][n] = (f32x4){0.f, 0.f, 0.f, 0.f};
;         cur = nxt; cA = nA; cB = nB; ++ui;
;         if constexpr (ALIGN_EPI) { if (wr == 1) PG8_BAR; }
.LBB0_225:
	s_and_b64 vcc, exec, s[40:41]
	s_mov_b32 s33, s84
	s_mov_b32 s93, s95
	s_mov_b64 s[48:49], s[36:37]
	s_mov_b64 s[46:47], s[62:63]
	s_cbranch_vccnz .LBB0_358
	v_readlane_b32 s4, v255, 5
	s_cmpk_gt_u32 s4, 0xff
	s_cbranch_scc0 .Lres_align_b
	s_barrier
.Lres_align_b:
.LBB0_226:
	s_add_i32 s3, s3, 1
	s_mul_i32 s4, s3, s72
	s_mul_hi_u32 s5, s3, s53
	s_add_i32 s5, s5, s4
	s_mul_i32 s4, s3, s53
	s_add_u32 s36, s4, s2
	s_addc_u32 s37, s5, s73
	s_waitcnt lgkmcnt(0)
	v_mov_b64_e32 v[0:1], s[8:9]
	v_cmp_ge_i64_e64 s[40:41], s[36:37], v[0:1]
	v_cmp_lt_i64_e64 s[42:43], s[36:37], v[0:1]
	s_and_b64 vcc, exec, s[40:41]
	s_cbranch_vccnz .LBB0_228
	s_not_b32 s4, s36
	s_add_i32 s4, s8, s4
	s_ashr_i32 s5, s4, 31
	s_lshr_b32 s5, s5, 29
	s_add_i32 s5, s4, s5
	s_ashr_i32 s6, s5, 3
	s_and_b32 s5, s5, -8
	s_sub_i32 s4, s4, s5
	v_readlane_b32 s5, v255, 20
	s_xor_b32 s4, s4, s5
	s_lshr_b32 s5, s4, 31
	v_readlane_b32 s7, v255, 8
	s_or_b32 s5, s7, s5
	s_mul_i32 s4, s5, s4
	s_add_i32 s4, s4, s6
	s_abs_i32 s6, s4
	s_mul_hi_u32 s7, s6, s85
	s_mul_i32 s36, s7, s76
	s_ashr_i32 s5, s4, 31
	s_sub_i32 s6, s6, s36
	s_xor_b32 s5, s5, s77
	s_add_i32 s36, s7, 1
	s_sub_i32 s37, s6, s76
	s_cmp_ge_u32 s6, s76
	s_cselect_b32 s7, s36, s7
	s_cselect_b32 s6, s37, s6
	s_add_i32 s36, s7, 1
	s_cmp_ge_u32 s6, s76
	s_cselect_b32 s6, s36, s7
	s_xor_b32 s6, s6, s5
	s_sub_i32 s5, s6, s5
	s_lshl_b32 s6, s5, 3
	s_sub_i32 s7, 0x80, s6
	s_min_i32 s7, s7, 8
	s_abs_i32 s36, s7
	v_cvt_f32_u32_e32 v0, s36
	s_sub_i32 s44, 0, s36
	s_mul_i32 s5, s5, s75
	s_sub_i32 s4, s4, s5
	v_rcp_iflag_f32_e32 v0, v0
	s_abs_i32 s37, s4
	s_xor_b32 s5, s4, s7
	s_ashr_i32 s5, s5, 31
	v_mul_f32_e32 v0, 0x4f7ffffe, v0
	v_cvt_u32_f32_e32 v0, v0
	s_nop 0
	v_readfirstlane_b32 s45, v0
	s_mul_i32 s44, s44, s45
	s_mul_hi_u32 s44, s45, s44
	s_add_i32 s45, s45, s44
	s_mul_hi_u32 s44, s37, s45
	s_mul_i32 s45, s44, s36
	s_sub_i32 s37, s37, s45
	s_add_i32 s45, s44, 1
	s_sub_i32 s62, s37, s36
	s_cmp_ge_u32 s37, s36
	s_cselect_b32 s44, s45, s44
	s_cselect_b32 s37, s62, s37
	s_add_i32 s45, s44, 1
	s_cmp_ge_u32 s37, s36
	s_cselect_b32 s36, s45, s44
	s_xor_b32 s36, s36, s5
	s_sub_i32 s84, s36, s5
	s_mul_i32 s5, s84, s7
	s_sub_i32 s4, s4, s5
	s_add_i32 s95, s4, s6

; #define PG8_BAR __builtin_amdgcn_s_barrier()
; template <class Epi, class Sched, bool ALIGN_EPI = false, bool SP2 = false>
; __device__ __forceinline__ void gemm_phase(PG8_LAS unsigned char* lds, const Gemm g, const Sched& S, const Epi& E, const int tid_in) {
;     ...
;         if constexpr (ALIGN_EPI) { if (wr == 0) PG8_BAR; }
;         if constexpr (!Epi::AFTER_DRAIN) { E(acc, cur, wr, wc, fr, fq); S.done(cur); }
.LBB0_235:
	v_readlane_b32 s4, v255, 5
	s_cmpk_gt_u32 s4, 0xff
	s_cbranch_scc1 .Lres_align_a
	s_barrier

; #define PG8_WAIT_V(n) asm volatile("s_waitcnt vmcnt(" #n ")" ::: "memory")
; #define PG8_BAR __builtin_amdgcn_s_barrier()
; template <class Epi, class Sched, bool ALIGN_EPI = false, bool SP2 = false>
; __device__ __forceinline__ void gemm_phase(PG8_LAS unsigned char* lds, const Gemm g, const Sched& S, const Epi& E, const int tid_in) {
;     ...
;     PG8_WAIT_V(0);
;     if constexpr (!ALIGN_EPI) { if (wr == 0) PG8_BAR; }
;     PG8_BAR;
.LBB0_358:
	s_waitcnt vmcnt(0)
	v_readlane_b32 s0, v255, 5
	v_readlane_b32 s74, v254, 1
	v_readlane_b32 s82, v254, 5
	v_readlane_b32 s84, v254, 60
	v_readlane_b32 s68, v254, 55
	v_readlane_b32 s70, v254, 57
	s_cmpk_gt_u32 s0, 0xff
	v_readlane_b32 s72, v254, 0
	v_readlane_b32 s75, v254, 2
	v_readlane_b32 s76, v254, 3
	v_readlane_b32 s83, v254, 6
	v_readlane_b32 s73, v254, 59
	v_readlane_b32 s85, v254, 61
	v_readlane_b32 s69, v254, 56
	v_readlane_b32 s71, v254, 58
	s_mov_b32 s86, 0x200000
	s_mov_b32 s87, 0x201000
	s_movk_i32 s91, 0x3c0
	s_mov_b32 s95, 0xffffffe
	v_xor_b32_e32 v217, 8, v232
	v_readlane_b32 s77, v254, 4
	s_cbranch_scc1 .LBB0_360
.LBB0_360:
	v_readlane_b32 s14, v255, 6
	s_movk_i32 s77, 0x1000
	v_readlane_b32 s15, v255, 7
	v_xor_b32_e32 v214, 4, v232
	s_barrier
